# prep compress_item: token activations staged once per workgroup through LDS (coalesced, double buffered, one barrier per 256-k round) instead of per-wave gathers; W fragments two rounds in flight
# speedup vs baseline: 1.0210x; 1.0115x over previous
; #define MFMA16(a, b, c) __builtin_amdgcn_mfma_f32_16x16x32_bf16((a), (b), (c), 0, 0, 0)
; DI void compress_item(const Args& a, int l, int item, LAS unsigned char* lds) {
;     ...
;     const bf16_t* w1 = W + W_C1 + (size_t)kv * 262144 + (size_t)(wid * 16 + fr) * 2048 + fq * 8;
;     int tk0[2];
; #pragma unroll
;     for (int m = 0; m < 2; ++m) tk0[m] = 16 * (nq * 32 + m * 16 + fr);
; #pragma unroll 1
;     for (int k8 = 0; k8 < 64; k8 += 8) {
;         bf16x8 bfr[8], af[8][2];
; #pragma unroll
;         for (int kk = 0; kk < 8; ++kk) {
;             const int ks = k8 + kk, tokoff = ks >> 1, dcol = (ks & 1) * 32 + fq * 8;
;             bfr[kk] = *(const bf16x8*)(w1 + ks * 32);
; #pragma unroll
;             for (int m = 0; m < 2; ++m) { int tk = tk0[m] + tokoff; tk = tk > SEQ - 1 ? SEQ - 1 : tk; af[kk][m] = *(const bf16x8*)(PROJ + ((size_t)b * SEQ + tk) * PP + colbase + dcol); }
;         }
; #pragma unroll
;         for (int kk = 0; kk < 8; ++kk)
; #pragma unroll
;             for (int m = 0; m < 2; ++m) acc[m] = MFMA16(af[kk][m], bfr[kk], acc[m]);
.LBB0_604:
	v_lshl_add_u64 v[208:209], v[18:19], 0, v[12:13]
	s_and_b32 s14, s10, 7
	s_lshl_b32 s14, s14, 9
	v_bfe_u32 v181, v9, 5, 4
	v_bfe_u32 v182, v9, 3, 2
	v_and_b32_e32 v183, 7, v9
	v_lshl_add_u32 v178, v181, 4, v182
	v_add_u32_e32 v178, s14, v178
	v_lshlrev_b32_e32 v176, 4, v183
	v_sub_u32_e32 v176, v176, v12
	v_ashrrev_i32_e32 v177, 31, v176
	v_lshl_add_u64 v[252:253], v[14:15], 0, v[176:177]
	v_mul_u32_u24_e32 v179, 544, v181
	v_lshl_add_u32 v179, v182, 7, v179
	v_lshl_add_u32 v179, v183, 4, v179
	v_add_u32_e32 v179, 0x10000, v179
	v_mul_u32_u24_e32 v180, 544, v21
	v_lshl_add_u32 v180, v20, 4, v180
	v_add_u32_e32 v180, 0x10000, v180
	v_add_u32_e32 v251, 0, v178
	v_min_u32_e32 v251, 0xfff, v251
	v_or_b32_e32 v251, s6, v251
	v_mul_u32_u24_e32 v128, 0x1830, v251
	v_lshl_add_u64 v[254:255], v[252:253], 0, v[128:129]
	global_load_dwordx4 v[168:171], v[254:255], off
	v_add_u32_e32 v251, 0x100, v178
	v_min_u32_e32 v251, 0xfff, v251
	v_or_b32_e32 v251, s6, v251
	v_mul_u32_u24_e32 v128, 0x1830, v251
	v_lshl_add_u64 v[254:255], v[252:253], 0, v[128:129]
	global_load_dwordx4 v[172:175], v[254:255], off
	global_load_dwordx4 v[24:27], v[208:209], off offset:-256
	global_load_dwordx4 v[28:31], v[208:209], off offset:-192
	global_load_dwordx4 v[32:35], v[208:209], off offset:-128
	global_load_dwordx4 v[36:39], v[208:209], off offset:-64
	global_load_dwordx4 v[40:43], v[208:209], off
	global_load_dwordx4 v[44:47], v[208:209], off offset:64
	global_load_dwordx4 v[48:51], v[208:209], off offset:128
	global_load_dwordx4 v[52:55], v[208:209], off offset:192
	global_load_dwordx4 v[56:59], v[208:209], off offset:256
	global_load_dwordx4 v[60:63], v[208:209], off offset:320
	global_load_dwordx4 v[64:67], v[208:209], off offset:384
	global_load_dwordx4 v[68:71], v[208:209], off offset:448
	global_load_dwordx4 v[72:75], v[208:209], off offset:512
	global_load_dwordx4 v[76:79], v[208:209], off offset:576
	global_load_dwordx4 v[80:83], v[208:209], off offset:640
	global_load_dwordx4 v[84:87], v[208:209], off offset:704
	s_waitcnt vmcnt(16)
	ds_write_b128 v179, v[168:171] offset:0
	ds_write_b128 v179, v[172:175] offset:8704
	v_add_u32_e32 v251, 4, v178
	v_min_u32_e32 v251, 0xfff, v251
	v_or_b32_e32 v251, s6, v251
	v_mul_u32_u24_e32 v128, 0x1830, v251
	v_lshl_add_u64 v[254:255], v[252:253], 0, v[128:129]
	global_load_dwordx4 v[168:171], v[254:255], off
	v_add_u32_e32 v251, 0x104, v178
	v_min_u32_e32 v251, 0xfff, v251
	v_or_b32_e32 v251, s6, v251
	v_mul_u32_u24_e32 v128, 0x1830, v251
	v_lshl_add_u64 v[254:255], v[252:253], 0, v[128:129]
	global_load_dwordx4 v[172:175], v[254:255], off
	s_waitcnt lgkmcnt(0)
	s_barrier
	ds_read_b128 v[88:91], v180 offset:0
	ds_read_b128 v[92:95], v180 offset:8704
	ds_read_b128 v[96:99], v180 offset:64
	ds_read_b128 v[100:103], v180 offset:8768
	ds_read_b128 v[104:107], v180 offset:128
	ds_read_b128 v[108:111], v180 offset:8832
	ds_read_b128 v[112:115], v180 offset:192
	ds_read_b128 v[116:119], v180 offset:8896
	ds_read_b128 v[120:123], v180 offset:256
	ds_read_b128 v[124:127], v180 offset:8960
	ds_read_b128 v[130:133], v180 offset:320
	ds_read_b128 v[134:137], v180 offset:9024
	ds_read_b128 v[138:141], v180 offset:384
	ds_read_b128 v[142:145], v180 offset:9088
	ds_read_b128 v[146:149], v180 offset:448
	ds_read_b128 v[150:153], v180 offset:9152
	s_waitcnt vmcnt(17)
	s_waitcnt lgkmcnt(15)
	v_mfma_f32_16x16x32_bf16 v[4:7], v[88:91], v[24:27], v[4:7]
	s_waitcnt lgkmcnt(14)
	v_mfma_f32_16x16x32_bf16 v[0:3], v[92:95], v[24:27], v[0:3]
	s_waitcnt vmcnt(16)
	s_waitcnt lgkmcnt(13)
	v_mfma_f32_16x16x32_bf16 v[4:7], v[96:99], v[28:31], v[4:7]
	s_waitcnt lgkmcnt(12)
	v_mfma_f32_16x16x32_bf16 v[0:3], v[100:103], v[28:31], v[0:3]
	s_waitcnt vmcnt(15)
	s_waitcnt lgkmcnt(11)
	v_mfma_f32_16x16x32_bf16 v[4:7], v[104:107], v[32:35], v[4:7]
	s_waitcnt lgkmcnt(10)
	v_mfma_f32_16x16x32_bf16 v[0:3], v[108:111], v[32:35], v[0:3]
	s_waitcnt vmcnt(14)
	s_waitcnt lgkmcnt(9)
	v_mfma_f32_16x16x32_bf16 v[4:7], v[112:115], v[36:39], v[4:7]
	s_waitcnt lgkmcnt(8)
	v_mfma_f32_16x16x32_bf16 v[0:3], v[116:119], v[36:39], v[0:3]
	s_waitcnt vmcnt(13)
	s_waitcnt lgkmcnt(7)
	v_mfma_f32_16x16x32_bf16 v[4:7], v[120:123], v[40:43], v[4:7]
	s_waitcnt lgkmcnt(6)
	v_mfma_f32_16x16x32_bf16 v[0:3], v[124:127], v[40:43], v[0:3]
	s_waitcnt vmcnt(12)
	s_waitcnt lgkmcnt(5)
	v_mfma_f32_16x16x32_bf16 v[4:7], v[130:133], v[44:47], v[4:7]
	s_waitcnt lgkmcnt(4)
	v_mfma_f32_16x16x32_bf16 v[0:3], v[134:137], v[44:47], v[0:3]
	s_waitcnt vmcnt(11)
	s_waitcnt lgkmcnt(3)
	v_mfma_f32_16x16x32_bf16 v[4:7], v[138:141], v[48:51], v[4:7]
	s_waitcnt lgkmcnt(2)
	v_mfma_f32_16x16x32_bf16 v[0:3], v[142:145], v[48:51], v[0:3]
	s_waitcnt vmcnt(10)
	s_waitcnt lgkmcnt(1)
	v_mfma_f32_16x16x32_bf16 v[4:7], v[146:149], v[52:55], v[4:7]
	s_waitcnt lgkmcnt(0)
	v_mfma_f32_16x16x32_bf16 v[0:3], v[150:153], v[52:55], v[0:3]
	global_load_dwordx4 v[24:27], v[208:209], off offset:768
	global_load_dwordx4 v[28:31], v[208:209], off offset:832
	global_load_dwordx4 v[32:35], v[208:209], off offset:896
	global_load_dwordx4 v[36:39], v[208:209], off offset:960
	global_load_dwordx4 v[40:43], v[208:209], off offset:1024
	global_load_dwordx4 v[44:47], v[208:209], off offset:1088
	global_load_dwordx4 v[48:51], v[208:209], off offset:1152
	global_load_dwordx4 v[52:55], v[208:209], off offset:1216
	s_waitcnt vmcnt(8)
	ds_write_b128 v179, v[168:171] offset:17408
	ds_write_b128 v179, v[172:175] offset:26112
	v_add_u32_e32 v251, 8, v178
	v_min_u32_e32 v251, 0xfff, v251
	v_or_b32_e32 v251, s6, v251
	v_mul_u32_u24_e32 v128, 0x1830, v251
	v_lshl_add_u64 v[254:255], v[252:253], 0, v[128:129]
	global_load_dwordx4 v[168:171], v[254:255], off
	v_add_u32_e32 v251, 0x108, v178
	v_min_u32_e32 v251, 0xfff, v251
	v_or_b32_e32 v251, s6, v251
	v_mul_u32_u24_e32 v128, 0x1830, v251
	v_lshl_add_u64 v[254:255], v[252:253], 0, v[128:129]
	global_load_dwordx4 v[172:175], v[254:255], off
	s_waitcnt lgkmcnt(0)
	s_barrier
; #define MFMA16(a, b, c) __builtin_amdgcn_mfma_f32_16x16x32_bf16((a), (b), (c), 0, 0, 0)
; DI void compress_item(const Args& a, int l, int item, LAS unsigned char* lds) {
;     ...
; #pragma unroll 1
;     for (int k8 = 0; k8 < 64; k8 += 8) {
;         bf16x8 bfr[8], af[8][2];
; #pragma unroll
;         for (int kk = 0; kk < 8; ++kk) {
;             const int ks = k8 + kk, tokoff = ks >> 1, dcol = (ks & 1) * 32 + fq * 8;
;             bfr[kk] = *(const bf16x8*)(w1 + ks * 32);
; #pragma unroll
;             for (int m = 0; m < 2; ++m) { int tk = tk0[m] + tokoff; tk = tk > SEQ - 1 ? SEQ - 1 : tk; af[kk][m] = *(const bf16x8*)(PROJ + ((size_t)b * SEQ + tk) * PP + colbase + dcol); }
;         }
; #pragma unroll
;         for (int kk = 0; kk < 8; ++kk)
; #pragma unroll
;             for (int m = 0; m < 2; ++m) acc[m] = MFMA16(af[kk][m], bfr[kk], acc[m]);
	ds_read_b128 v[88:91], v180 offset:17408
	ds_read_b128 v[92:95], v180 offset:26112
	ds_read_b128 v[96:99], v180 offset:17472
	ds_read_b128 v[100:103], v180 offset:26176
	ds_read_b128 v[104:107], v180 offset:17536
	ds_read_b128 v[108:111], v180 offset:26240
	ds_read_b128 v[112:115], v180 offset:17600
	ds_read_b128 v[116:119], v180 offset:26304
	ds_read_b128 v[120:123], v180 offset:17664
	ds_read_b128 v[124:127], v180 offset:26368
	ds_read_b128 v[130:133], v180 offset:17728
	ds_read_b128 v[134:137], v180 offset:26432
	ds_read_b128 v[138:141], v180 offset:17792
	ds_read_b128 v[142:145], v180 offset:26496
	ds_read_b128 v[146:149], v180 offset:17856
	ds_read_b128 v[150:153], v180 offset:26560
	s_waitcnt vmcnt(19)
	s_waitcnt lgkmcnt(15)
	v_mfma_f32_16x16x32_bf16 v[4:7], v[88:91], v[56:59], v[4:7]
	s_waitcnt lgkmcnt(14)
	v_mfma_f32_16x16x32_bf16 v[0:3], v[92:95], v[56:59], v[0:3]
	s_waitcnt vmcnt(18)
	s_waitcnt lgkmcnt(13)
	v_mfma_f32_16x16x32_bf16 v[4:7], v[96:99], v[60:63], v[4:7]
	s_waitcnt lgkmcnt(12)
	v_mfma_f32_16x16x32_bf16 v[0:3], v[100:103], v[60:63], v[0:3]
	s_waitcnt vmcnt(17)
	s_waitcnt lgkmcnt(11)
	v_mfma_f32_16x16x32_bf16 v[4:7], v[104:107], v[64:67], v[4:7]
	s_waitcnt lgkmcnt(10)
	v_mfma_f32_16x16x32_bf16 v[0:3], v[108:111], v[64:67], v[0:3]
	s_waitcnt vmcnt(16)
	s_waitcnt lgkmcnt(9)
	v_mfma_f32_16x16x32_bf16 v[4:7], v[112:115], v[68:71], v[4:7]
	s_waitcnt lgkmcnt(8)
	v_mfma_f32_16x16x32_bf16 v[0:3], v[116:119], v[68:71], v[0:3]
	s_waitcnt vmcnt(15)
	s_waitcnt lgkmcnt(7)
	v_mfma_f32_16x16x32_bf16 v[4:7], v[120:123], v[72:75], v[4:7]
	s_waitcnt lgkmcnt(6)
	v_mfma_f32_16x16x32_bf16 v[0:3], v[124:127], v[72:75], v[0:3]
	s_waitcnt vmcnt(14)
	s_waitcnt lgkmcnt(5)
	v_mfma_f32_16x16x32_bf16 v[4:7], v[130:133], v[76:79], v[4:7]
	s_waitcnt lgkmcnt(4)
	v_mfma_f32_16x16x32_bf16 v[0:3], v[134:137], v[76:79], v[0:3]
	s_waitcnt vmcnt(13)
	s_waitcnt lgkmcnt(3)
	v_mfma_f32_16x16x32_bf16 v[4:7], v[138:141], v[80:83], v[4:7]
	s_waitcnt lgkmcnt(2)
	v_mfma_f32_16x16x32_bf16 v[0:3], v[142:145], v[80:83], v[0:3]
	s_waitcnt vmcnt(12)
	s_waitcnt lgkmcnt(1)
	v_mfma_f32_16x16x32_bf16 v[4:7], v[146:149], v[84:87], v[4:7]
	s_waitcnt lgkmcnt(0)
	v_mfma_f32_16x16x32_bf16 v[0:3], v[150:153], v[84:87], v[0:3]
	global_load_dwordx4 v[56:59], v[208:209], off offset:1280
	global_load_dwordx4 v[60:63], v[208:209], off offset:1344
	global_load_dwordx4 v[64:67], v[208:209], off offset:1408
	global_load_dwordx4 v[68:71], v[208:209], off offset:1472
	global_load_dwordx4 v[72:75], v[208:209], off offset:1536
	global_load_dwordx4 v[76:79], v[208:209], off offset:1600
	global_load_dwordx4 v[80:83], v[208:209], off offset:1664
	global_load_dwordx4 v[84:87], v[208:209], off offset:1728
	s_waitcnt vmcnt(8)
	ds_write_b128 v179, v[168:171] offset:0
	ds_write_b128 v179, v[172:175] offset:8704
	v_add_u32_e32 v251, 12, v178
	v_min_u32_e32 v251, 0xfff, v251
	v_or_b32_e32 v251, s6, v251
	v_mul_u32_u24_e32 v128, 0x1830, v251
	v_lshl_add_u64 v[254:255], v[252:253], 0, v[128:129]
	global_load_dwordx4 v[168:171], v[254:255], off
	v_add_u32_e32 v251, 0x10c, v178
	v_min_u32_e32 v251, 0xfff, v251
	v_or_b32_e32 v251, s6, v251
	v_mul_u32_u24_e32 v128, 0x1830, v251
	v_lshl_add_u64 v[254:255], v[252:253], 0, v[128:129]
	global_load_dwordx4 v[172:175], v[254:255], off
	s_waitcnt lgkmcnt(0)
	s_barrier
	ds_read_b128 v[88:91], v180 offset:0
	ds_read_b128 v[92:95], v180 offset:8704
	ds_read_b128 v[96:99], v180 offset:64
	ds_read_b128 v[100:103], v180 offset:8768
	ds_read_b128 v[104:107], v180 offset:128
	ds_read_b128 v[108:111], v180 offset:8832
	ds_read_b128 v[112:115], v180 offset:192
	ds_read_b128 v[116:119], v180 offset:8896
	ds_read_b128 v[120:123], v180 offset:256
	ds_read_b128 v[124:127], v180 offset:8960
	ds_read_b128 v[130:133], v180 offset:320
	ds_read_b128 v[134:137], v180 offset:9024
	ds_read_b128 v[138:141], v180 offset:384
	ds_read_b128 v[142:145], v180 offset:9088
	ds_read_b128 v[146:149], v180 offset:448
	ds_read_b128 v[150:153], v180 offset:9152
	s_waitcnt vmcnt(19)
	s_waitcnt lgkmcnt(15)
	v_mfma_f32_16x16x32_bf16 v[4:7], v[88:91], v[24:27], v[4:7]
	s_waitcnt lgkmcnt(14)
	v_mfma_f32_16x16x32_bf16 v[0:3], v[92:95], v[24:27], v[0:3]
	s_waitcnt vmcnt(18)
	s_waitcnt lgkmcnt(13)
	v_mfma_f32_16x16x32_bf16 v[4:7], v[96:99], v[28:31], v[4:7]
	s_waitcnt lgkmcnt(12)
	v_mfma_f32_16x16x32_bf16 v[0:3], v[100:103], v[28:31], v[0:3]
	s_waitcnt vmcnt(17)
	s_waitcnt lgkmcnt(11)
	v_mfma_f32_16x16x32_bf16 v[4:7], v[104:107], v[32:35], v[4:7]
	s_waitcnt lgkmcnt(10)
	v_mfma_f32_16x16x32_bf16 v[0:3], v[108:111], v[32:35], v[0:3]
	s_waitcnt vmcnt(16)
	s_waitcnt lgkmcnt(9)
	v_mfma_f32_16x16x32_bf16 v[4:7], v[112:115], v[36:39], v[4:7]
	s_waitcnt lgkmcnt(8)
	v_mfma_f32_16x16x32_bf16 v[0:3], v[116:119], v[36:39], v[0:3]
	s_waitcnt vmcnt(15)
	s_waitcnt lgkmcnt(7)
	v_mfma_f32_16x16x32_bf16 v[4:7], v[120:123], v[40:43], v[4:7]
	s_waitcnt lgkmcnt(6)
	v_mfma_f32_16x16x32_bf16 v[0:3], v[124:127], v[40:43], v[0:3]
	s_waitcnt vmcnt(14)
	s_waitcnt lgkmcnt(5)
	v_mfma_f32_16x16x32_bf16 v[4:7], v[130:133], v[44:47], v[4:7]
	s_waitcnt lgkmcnt(4)
	v_mfma_f32_16x16x32_bf16 v[0:3], v[134:137], v[44:47], v[0:3]
	s_waitcnt vmcnt(13)
	s_waitcnt lgkmcnt(3)
	v_mfma_f32_16x16x32_bf16 v[4:7], v[138:141], v[48:51], v[4:7]
	s_waitcnt lgkmcnt(2)
	v_mfma_f32_16x16x32_bf16 v[0:3], v[142:145], v[48:51], v[0:3]
	s_waitcnt vmcnt(12)
	s_waitcnt lgkmcnt(1)
	v_mfma_f32_16x16x32_bf16 v[4:7], v[146:149], v[52:55], v[4:7]
	s_waitcnt lgkmcnt(0)
	v_mfma_f32_16x16x32_bf16 v[0:3], v[150:153], v[52:55], v[0:3]
	global_load_dwordx4 v[24:27], v[208:209], off offset:1792
	global_load_dwordx4 v[28:31], v[208:209], off offset:1856
	global_load_dwordx4 v[32:35], v[208:209], off offset:1920
	global_load_dwordx4 v[36:39], v[208:209], off offset:1984
	global_load_dwordx4 v[40:43], v[208:209], off offset:2048
	global_load_dwordx4 v[44:47], v[208:209], off offset:2112
	global_load_dwordx4 v[48:51], v[208:209], off offset:2176
	global_load_dwordx4 v[52:55], v[208:209], off offset:2240
	s_waitcnt vmcnt(8)
	ds_write_b128 v179, v[168:171] offset:17408
	ds_write_b128 v179, v[172:175] offset:26112
	v_add_u32_e32 v251, 16, v178
	v_min_u32_e32 v251, 0xfff, v251
	v_or_b32_e32 v251, s6, v251
	v_mul_u32_u24_e32 v128, 0x1830, v251
	v_lshl_add_u64 v[254:255], v[252:253], 0, v[128:129]
	global_load_dwordx4 v[168:171], v[254:255], off
	v_add_u32_e32 v251, 0x110, v178
	v_min_u32_e32 v251, 0xfff, v251
	v_or_b32_e32 v251, s6, v251
	v_mul_u32_u24_e32 v128, 0x1830, v251
	v_lshl_add_u64 v[254:255], v[252:253], 0, v[128:129]
	global_load_dwordx4 v[172:175], v[254:255], off
	s_waitcnt lgkmcnt(0)
	s_barrier
; #define MFMA16(a, b, c) __builtin_amdgcn_mfma_f32_16x16x32_bf16((a), (b), (c), 0, 0, 0)
; DI void compress_item(const Args& a, int l, int item, LAS unsigned char* lds) {
;     ...
; #pragma unroll 1
;     for (int k8 = 0; k8 < 64; k8 += 8) {
;         bf16x8 bfr[8], af[8][2];
; #pragma unroll
;         for (int kk = 0; kk < 8; ++kk) {
;             const int ks = k8 + kk, tokoff = ks >> 1, dcol = (ks & 1) * 32 + fq * 8;
;             bfr[kk] = *(const bf16x8*)(w1 + ks * 32);
; #pragma unroll
;             for (int m = 0; m < 2; ++m) { int tk = tk0[m] + tokoff; tk = tk > SEQ - 1 ? SEQ - 1 : tk; af[kk][m] = *(const bf16x8*)(PROJ + ((size_t)b * SEQ + tk) * PP + colbase + dcol); }
;         }
; #pragma unroll
;         for (int kk = 0; kk < 8; ++kk)
; #pragma unroll
;             for (int m = 0; m < 2; ++m) acc[m] = MFMA16(af[kk][m], bfr[kk], acc[m]);
	ds_read_b128 v[88:91], v180 offset:17408
	ds_read_b128 v[92:95], v180 offset:26112
	ds_read_b128 v[96:99], v180 offset:17472
	ds_read_b128 v[100:103], v180 offset:26176
	ds_read_b128 v[104:107], v180 offset:17536
	ds_read_b128 v[108:111], v180 offset:26240
	ds_read_b128 v[112:115], v180 offset:17600
	ds_read_b128 v[116:119], v180 offset:26304
	ds_read_b128 v[120:123], v180 offset:17664
	ds_read_b128 v[124:127], v180 offset:26368
	ds_read_b128 v[130:133], v180 offset:17728
	ds_read_b128 v[134:137], v180 offset:26432
	ds_read_b128 v[138:141], v180 offset:17792
	ds_read_b128 v[142:145], v180 offset:26496
	ds_read_b128 v[146:149], v180 offset:17856
	ds_read_b128 v[150:153], v180 offset:26560
	s_waitcnt vmcnt(19)
	s_waitcnt lgkmcnt(15)
	v_mfma_f32_16x16x32_bf16 v[4:7], v[88:91], v[56:59], v[4:7]
	s_waitcnt lgkmcnt(14)
	v_mfma_f32_16x16x32_bf16 v[0:3], v[92:95], v[56:59], v[0:3]
	s_waitcnt vmcnt(18)
	s_waitcnt lgkmcnt(13)
	v_mfma_f32_16x16x32_bf16 v[4:7], v[96:99], v[60:63], v[4:7]
	s_waitcnt lgkmcnt(12)
	v_mfma_f32_16x16x32_bf16 v[0:3], v[100:103], v[60:63], v[0:3]
	s_waitcnt vmcnt(17)
	s_waitcnt lgkmcnt(11)
	v_mfma_f32_16x16x32_bf16 v[4:7], v[104:107], v[64:67], v[4:7]
	s_waitcnt lgkmcnt(10)
	v_mfma_f32_16x16x32_bf16 v[0:3], v[108:111], v[64:67], v[0:3]
	s_waitcnt vmcnt(16)
	s_waitcnt lgkmcnt(9)
	v_mfma_f32_16x16x32_bf16 v[4:7], v[112:115], v[68:71], v[4:7]
	s_waitcnt lgkmcnt(8)
	v_mfma_f32_16x16x32_bf16 v[0:3], v[116:119], v[68:71], v[0:3]
	s_waitcnt vmcnt(15)
	s_waitcnt lgkmcnt(7)
	v_mfma_f32_16x16x32_bf16 v[4:7], v[120:123], v[72:75], v[4:7]
	s_waitcnt lgkmcnt(6)
	v_mfma_f32_16x16x32_bf16 v[0:3], v[124:127], v[72:75], v[0:3]
	s_waitcnt vmcnt(14)
	s_waitcnt lgkmcnt(5)
	v_mfma_f32_16x16x32_bf16 v[4:7], v[130:133], v[76:79], v[4:7]
	s_waitcnt lgkmcnt(4)
	v_mfma_f32_16x16x32_bf16 v[0:3], v[134:137], v[76:79], v[0:3]
	s_waitcnt vmcnt(13)
	s_waitcnt lgkmcnt(3)
	v_mfma_f32_16x16x32_bf16 v[4:7], v[138:141], v[80:83], v[4:7]
	s_waitcnt lgkmcnt(2)
	v_mfma_f32_16x16x32_bf16 v[0:3], v[142:145], v[80:83], v[0:3]
	s_waitcnt vmcnt(12)
	s_waitcnt lgkmcnt(1)
	v_mfma_f32_16x16x32_bf16 v[4:7], v[146:149], v[84:87], v[4:7]
	s_waitcnt lgkmcnt(0)
	v_mfma_f32_16x16x32_bf16 v[0:3], v[150:153], v[84:87], v[0:3]
	global_load_dwordx4 v[56:59], v[208:209], off offset:2304
	global_load_dwordx4 v[60:63], v[208:209], off offset:2368
	global_load_dwordx4 v[64:67], v[208:209], off offset:2432
	global_load_dwordx4 v[68:71], v[208:209], off offset:2496
	global_load_dwordx4 v[72:75], v[208:209], off offset:2560
	global_load_dwordx4 v[76:79], v[208:209], off offset:2624
	global_load_dwordx4 v[80:83], v[208:209], off offset:2688
	global_load_dwordx4 v[84:87], v[208:209], off offset:2752
	s_waitcnt vmcnt(8)
	ds_write_b128 v179, v[168:171] offset:0
	ds_write_b128 v179, v[172:175] offset:8704
	v_add_u32_e32 v251, 20, v178
	v_min_u32_e32 v251, 0xfff, v251
	v_or_b32_e32 v251, s6, v251
	v_mul_u32_u24_e32 v128, 0x1830, v251
	v_lshl_add_u64 v[254:255], v[252:253], 0, v[128:129]
	global_load_dwordx4 v[168:171], v[254:255], off
	v_add_u32_e32 v251, 0x114, v178
	v_min_u32_e32 v251, 0xfff, v251
	v_or_b32_e32 v251, s6, v251
	v_mul_u32_u24_e32 v128, 0x1830, v251
	v_lshl_add_u64 v[254:255], v[252:253], 0, v[128:129]
	global_load_dwordx4 v[172:175], v[254:255], off
	s_waitcnt lgkmcnt(0)
	s_barrier
	ds_read_b128 v[88:91], v180 offset:0
	ds_read_b128 v[92:95], v180 offset:8704
	ds_read_b128 v[96:99], v180 offset:64
	ds_read_b128 v[100:103], v180 offset:8768
	ds_read_b128 v[104:107], v180 offset:128
	ds_read_b128 v[108:111], v180 offset:8832
	ds_read_b128 v[112:115], v180 offset:192
	ds_read_b128 v[116:119], v180 offset:8896
	ds_read_b128 v[120:123], v180 offset:256
	ds_read_b128 v[124:127], v180 offset:8960
	ds_read_b128 v[130:133], v180 offset:320
	ds_read_b128 v[134:137], v180 offset:9024
	ds_read_b128 v[138:141], v180 offset:384
	ds_read_b128 v[142:145], v180 offset:9088
	ds_read_b128 v[146:149], v180 offset:448
	ds_read_b128 v[150:153], v180 offset:9152
	s_waitcnt vmcnt(19)
	s_waitcnt lgkmcnt(15)
	v_mfma_f32_16x16x32_bf16 v[4:7], v[88:91], v[24:27], v[4:7]
	s_waitcnt lgkmcnt(14)
	v_mfma_f32_16x16x32_bf16 v[0:3], v[92:95], v[24:27], v[0:3]
	s_waitcnt vmcnt(18)
	s_waitcnt lgkmcnt(13)
	v_mfma_f32_16x16x32_bf16 v[4:7], v[96:99], v[28:31], v[4:7]
	s_waitcnt lgkmcnt(12)
	v_mfma_f32_16x16x32_bf16 v[0:3], v[100:103], v[28:31], v[0:3]
	s_waitcnt vmcnt(17)
	s_waitcnt lgkmcnt(11)
	v_mfma_f32_16x16x32_bf16 v[4:7], v[104:107], v[32:35], v[4:7]
	s_waitcnt lgkmcnt(10)
	v_mfma_f32_16x16x32_bf16 v[0:3], v[108:111], v[32:35], v[0:3]
	s_waitcnt vmcnt(16)
	s_waitcnt lgkmcnt(9)
	v_mfma_f32_16x16x32_bf16 v[4:7], v[112:115], v[36:39], v[4:7]
	s_waitcnt lgkmcnt(8)
	v_mfma_f32_16x16x32_bf16 v[0:3], v[116:119], v[36:39], v[0:3]
	s_waitcnt vmcnt(15)
	s_waitcnt lgkmcnt(7)
	v_mfma_f32_16x16x32_bf16 v[4:7], v[120:123], v[40:43], v[4:7]
	s_waitcnt lgkmcnt(6)
	v_mfma_f32_16x16x32_bf16 v[0:3], v[124:127], v[40:43], v[0:3]
	s_waitcnt vmcnt(14)
	s_waitcnt lgkmcnt(5)
	v_mfma_f32_16x16x32_bf16 v[4:7], v[130:133], v[44:47], v[4:7]
	s_waitcnt lgkmcnt(4)
	v_mfma_f32_16x16x32_bf16 v[0:3], v[134:137], v[44:47], v[0:3]
	s_waitcnt vmcnt(13)
	s_waitcnt lgkmcnt(3)
	v_mfma_f32_16x16x32_bf16 v[4:7], v[138:141], v[48:51], v[4:7]
	s_waitcnt lgkmcnt(2)
	v_mfma_f32_16x16x32_bf16 v[0:3], v[142:145], v[48:51], v[0:3]
	s_waitcnt vmcnt(12)
	s_waitcnt lgkmcnt(1)
	v_mfma_f32_16x16x32_bf16 v[4:7], v[146:149], v[52:55], v[4:7]
	s_waitcnt lgkmcnt(0)
	v_mfma_f32_16x16x32_bf16 v[0:3], v[150:153], v[52:55], v[0:3]
	global_load_dwordx4 v[24:27], v[208:209], off offset:2816
	global_load_dwordx4 v[28:31], v[208:209], off offset:2880
	global_load_dwordx4 v[32:35], v[208:209], off offset:2944
	global_load_dwordx4 v[36:39], v[208:209], off offset:3008
	global_load_dwordx4 v[40:43], v[208:209], off offset:3072
	global_load_dwordx4 v[44:47], v[208:209], off offset:3136
	global_load_dwordx4 v[48:51], v[208:209], off offset:3200
	global_load_dwordx4 v[52:55], v[208:209], off offset:3264
	s_waitcnt vmcnt(8)
	ds_write_b128 v179, v[168:171] offset:17408
	ds_write_b128 v179, v[172:175] offset:26112
	v_add_u32_e32 v251, 24, v178
	v_min_u32_e32 v251, 0xfff, v251
	v_or_b32_e32 v251, s6, v251
	v_mul_u32_u24_e32 v128, 0x1830, v251
	v_lshl_add_u64 v[254:255], v[252:253], 0, v[128:129]
	global_load_dwordx4 v[168:171], v[254:255], off
	v_add_u32_e32 v251, 0x118, v178
	v_min_u32_e32 v251, 0xfff, v251
	v_or_b32_e32 v251, s6, v251
	v_mul_u32_u24_e32 v128, 0x1830, v251
	v_lshl_add_u64 v[254:255], v[252:253], 0, v[128:129]
	global_load_dwordx4 v[172:175], v[254:255], off
	s_waitcnt lgkmcnt(0)
	s_barrier
; #define MFMA16(a, b, c) __builtin_amdgcn_mfma_f32_16x16x32_bf16((a), (b), (c), 0, 0, 0)
; DI void compress_item(const Args& a, int l, int item, LAS unsigned char* lds) {
;     ...
; #pragma unroll 1
;     for (int k8 = 0; k8 < 64; k8 += 8) {
;         bf16x8 bfr[8], af[8][2];
; #pragma unroll
;         for (int kk = 0; kk < 8; ++kk) {
;             const int ks = k8 + kk, tokoff = ks >> 1, dcol = (ks & 1) * 32 + fq * 8;
;             bfr[kk] = *(const bf16x8*)(w1 + ks * 32);
; #pragma unroll
;             for (int m = 0; m < 2; ++m) { int tk = tk0[m] + tokoff; tk = tk > SEQ - 1 ? SEQ - 1 : tk; af[kk][m] = *(const bf16x8*)(PROJ + ((size_t)b * SEQ + tk) * PP + colbase + dcol); }
;         }
; #pragma unroll
;         for (int kk = 0; kk < 8; ++kk)
; #pragma unroll
;             for (int m = 0; m < 2; ++m) acc[m] = MFMA16(af[kk][m], bfr[kk], acc[m]);
	ds_read_b128 v[88:91], v180 offset:17408
	ds_read_b128 v[92:95], v180 offset:26112
	ds_read_b128 v[96:99], v180 offset:17472
	ds_read_b128 v[100:103], v180 offset:26176
	ds_read_b128 v[104:107], v180 offset:17536
	ds_read_b128 v[108:111], v180 offset:26240
	ds_read_b128 v[112:115], v180 offset:17600
	ds_read_b128 v[116:119], v180 offset:26304
	ds_read_b128 v[120:123], v180 offset:17664
	ds_read_b128 v[124:127], v180 offset:26368
	ds_read_b128 v[130:133], v180 offset:17728
	ds_read_b128 v[134:137], v180 offset:26432
	ds_read_b128 v[138:141], v180 offset:17792
	ds_read_b128 v[142:145], v180 offset:26496
	ds_read_b128 v[146:149], v180 offset:17856
	ds_read_b128 v[150:153], v180 offset:26560
	s_waitcnt vmcnt(19)
	s_waitcnt lgkmcnt(15)
	v_mfma_f32_16x16x32_bf16 v[4:7], v[88:91], v[56:59], v[4:7]
	s_waitcnt lgkmcnt(14)
	v_mfma_f32_16x16x32_bf16 v[0:3], v[92:95], v[56:59], v[0:3]
	s_waitcnt vmcnt(18)
	s_waitcnt lgkmcnt(13)
	v_mfma_f32_16x16x32_bf16 v[4:7], v[96:99], v[60:63], v[4:7]
	s_waitcnt lgkmcnt(12)
	v_mfma_f32_16x16x32_bf16 v[0:3], v[100:103], v[60:63], v[0:3]
	s_waitcnt vmcnt(17)
	s_waitcnt lgkmcnt(11)
	v_mfma_f32_16x16x32_bf16 v[4:7], v[104:107], v[64:67], v[4:7]
	s_waitcnt lgkmcnt(10)
	v_mfma_f32_16x16x32_bf16 v[0:3], v[108:111], v[64:67], v[0:3]
	s_waitcnt vmcnt(16)
	s_waitcnt lgkmcnt(9)
	v_mfma_f32_16x16x32_bf16 v[4:7], v[112:115], v[68:71], v[4:7]
	s_waitcnt lgkmcnt(8)
	v_mfma_f32_16x16x32_bf16 v[0:3], v[116:119], v[68:71], v[0:3]
	s_waitcnt vmcnt(15)
	s_waitcnt lgkmcnt(7)
	v_mfma_f32_16x16x32_bf16 v[4:7], v[120:123], v[72:75], v[4:7]
	s_waitcnt lgkmcnt(6)
	v_mfma_f32_16x16x32_bf16 v[0:3], v[124:127], v[72:75], v[0:3]
	s_waitcnt vmcnt(14)
	s_waitcnt lgkmcnt(5)
	v_mfma_f32_16x16x32_bf16 v[4:7], v[130:133], v[76:79], v[4:7]
	s_waitcnt lgkmcnt(4)
	v_mfma_f32_16x16x32_bf16 v[0:3], v[134:137], v[76:79], v[0:3]
	s_waitcnt vmcnt(13)
	s_waitcnt lgkmcnt(3)
	v_mfma_f32_16x16x32_bf16 v[4:7], v[138:141], v[80:83], v[4:7]
	s_waitcnt lgkmcnt(2)
	v_mfma_f32_16x16x32_bf16 v[0:3], v[142:145], v[80:83], v[0:3]
	s_waitcnt vmcnt(12)
	s_waitcnt lgkmcnt(1)
	v_mfma_f32_16x16x32_bf16 v[4:7], v[146:149], v[84:87], v[4:7]
	s_waitcnt lgkmcnt(0)
	v_mfma_f32_16x16x32_bf16 v[0:3], v[150:153], v[84:87], v[0:3]
	global_load_dwordx4 v[56:59], v[208:209], off offset:3328
	global_load_dwordx4 v[60:63], v[208:209], off offset:3392
	global_load_dwordx4 v[64:67], v[208:209], off offset:3456
	global_load_dwordx4 v[68:71], v[208:209], off offset:3520
	global_load_dwordx4 v[72:75], v[208:209], off offset:3584
	global_load_dwordx4 v[76:79], v[208:209], off offset:3648
	global_load_dwordx4 v[80:83], v[208:209], off offset:3712
	global_load_dwordx4 v[84:87], v[208:209], off offset:3776
	s_waitcnt vmcnt(8)
	ds_write_b128 v179, v[168:171] offset:0
	ds_write_b128 v179, v[172:175] offset:8704
	v_add_u32_e32 v251, 28, v178
	v_min_u32_e32 v251, 0xfff, v251
	v_or_b32_e32 v251, s6, v251
	v_mul_u32_u24_e32 v128, 0x1830, v251
	v_lshl_add_u64 v[254:255], v[252:253], 0, v[128:129]
	global_load_dwordx4 v[168:171], v[254:255], off
	v_add_u32_e32 v251, 0x11c, v178
	v_min_u32_e32 v251, 0xfff, v251
	v_or_b32_e32 v251, s6, v251
	v_mul_u32_u24_e32 v128, 0x1830, v251
	v_lshl_add_u64 v[254:255], v[252:253], 0, v[128:129]
	global_load_dwordx4 v[172:175], v[254:255], off
	s_waitcnt lgkmcnt(0)
	s_barrier
	ds_read_b128 v[88:91], v180 offset:0
	ds_read_b128 v[92:95], v180 offset:8704
	ds_read_b128 v[96:99], v180 offset:64
	ds_read_b128 v[100:103], v180 offset:8768
	ds_read_b128 v[104:107], v180 offset:128
	ds_read_b128 v[108:111], v180 offset:8832
	ds_read_b128 v[112:115], v180 offset:192
	ds_read_b128 v[116:119], v180 offset:8896
	ds_read_b128 v[120:123], v180 offset:256
	ds_read_b128 v[124:127], v180 offset:8960
	ds_read_b128 v[130:133], v180 offset:320
	ds_read_b128 v[134:137], v180 offset:9024
	ds_read_b128 v[138:141], v180 offset:384
	ds_read_b128 v[142:145], v180 offset:9088
	ds_read_b128 v[146:149], v180 offset:448
	ds_read_b128 v[150:153], v180 offset:9152
	s_waitcnt vmcnt(19)
	s_waitcnt lgkmcnt(15)
	v_mfma_f32_16x16x32_bf16 v[4:7], v[88:91], v[24:27], v[4:7]
	s_waitcnt lgkmcnt(14)
	v_mfma_f32_16x16x32_bf16 v[0:3], v[92:95], v[24:27], v[0:3]
	s_waitcnt vmcnt(18)
	s_waitcnt lgkmcnt(13)
	v_mfma_f32_16x16x32_bf16 v[4:7], v[96:99], v[28:31], v[4:7]
	s_waitcnt lgkmcnt(12)
	v_mfma_f32_16x16x32_bf16 v[0:3], v[100:103], v[28:31], v[0:3]
	s_waitcnt vmcnt(17)
	s_waitcnt lgkmcnt(11)
	v_mfma_f32_16x16x32_bf16 v[4:7], v[104:107], v[32:35], v[4:7]
	s_waitcnt lgkmcnt(10)
	v_mfma_f32_16x16x32_bf16 v[0:3], v[108:111], v[32:35], v[0:3]
	s_waitcnt vmcnt(16)
	s_waitcnt lgkmcnt(9)
	v_mfma_f32_16x16x32_bf16 v[4:7], v[112:115], v[36:39], v[4:7]
	s_waitcnt lgkmcnt(8)
	v_mfma_f32_16x16x32_bf16 v[0:3], v[116:119], v[36:39], v[0:3]
	s_waitcnt vmcnt(15)
	s_waitcnt lgkmcnt(7)
	v_mfma_f32_16x16x32_bf16 v[4:7], v[120:123], v[40:43], v[4:7]
	s_waitcnt lgkmcnt(6)
	v_mfma_f32_16x16x32_bf16 v[0:3], v[124:127], v[40:43], v[0:3]
	s_waitcnt vmcnt(14)
	s_waitcnt lgkmcnt(5)
	v_mfma_f32_16x16x32_bf16 v[4:7], v[130:133], v[44:47], v[4:7]
	s_waitcnt lgkmcnt(4)
	v_mfma_f32_16x16x32_bf16 v[0:3], v[134:137], v[44:47], v[0:3]
	s_waitcnt vmcnt(13)
	s_waitcnt lgkmcnt(3)
	v_mfma_f32_16x16x32_bf16 v[4:7], v[138:141], v[48:51], v[4:7]
	s_waitcnt lgkmcnt(2)
	v_mfma_f32_16x16x32_bf16 v[0:3], v[142:145], v[48:51], v[0:3]
	s_waitcnt vmcnt(12)
	s_waitcnt lgkmcnt(1)
	v_mfma_f32_16x16x32_bf16 v[4:7], v[146:149], v[52:55], v[4:7]
	s_waitcnt lgkmcnt(0)
	v_mfma_f32_16x16x32_bf16 v[0:3], v[150:153], v[52:55], v[0:3]
	s_waitcnt vmcnt(0)
	ds_write_b128 v179, v[168:171] offset:17408
	ds_write_b128 v179, v[172:175] offset:26112
	s_waitcnt lgkmcnt(0)
	s_barrier
; #define MFMA16(a, b, c) __builtin_amdgcn_mfma_f32_16x16x32_bf16((a), (b), (c), 0, 0, 0)
; DI void compress_item(const Args& a, int l, int item, LAS unsigned char* lds) {
;     ...
; #pragma unroll
;         for (int kk = 0; kk < 8; ++kk)
; #pragma unroll
;             for (int m = 0; m < 2; ++m) acc[m] = MFMA16(af[kk][m], bfr[kk], acc[m]);
;     }
;     {
;         const int c = wid * 16 + fr; const float* biasp = (const float*)(a.ws + WS_BIASP) + kv * 16 * 128 + c;
;         float bias = 0.f;
; #pragma unroll
;         for (int kp = 0; kp < 16; ++kp) bias += biasp[kp * 128];
	ds_read_b128 v[88:91], v180 offset:17408
	ds_read_b128 v[92:95], v180 offset:26112
	ds_read_b128 v[96:99], v180 offset:17472
	ds_read_b128 v[100:103], v180 offset:26176
	ds_read_b128 v[104:107], v180 offset:17536
	ds_read_b128 v[108:111], v180 offset:26240
	ds_read_b128 v[112:115], v180 offset:17600
	ds_read_b128 v[116:119], v180 offset:26304
	ds_read_b128 v[120:123], v180 offset:17664
	ds_read_b128 v[124:127], v180 offset:26368
	ds_read_b128 v[130:133], v180 offset:17728
	ds_read_b128 v[134:137], v180 offset:26432
	ds_read_b128 v[138:141], v180 offset:17792
	ds_read_b128 v[142:145], v180 offset:26496
	ds_read_b128 v[146:149], v180 offset:17856
	ds_read_b128 v[150:153], v180 offset:26560
	s_waitcnt vmcnt(9)
	s_waitcnt lgkmcnt(15)
	v_mfma_f32_16x16x32_bf16 v[4:7], v[88:91], v[56:59], v[4:7]
	s_waitcnt lgkmcnt(14)
	v_mfma_f32_16x16x32_bf16 v[0:3], v[92:95], v[56:59], v[0:3]
	s_waitcnt vmcnt(8)
	s_waitcnt lgkmcnt(13)
	v_mfma_f32_16x16x32_bf16 v[4:7], v[96:99], v[60:63], v[4:7]
	s_waitcnt lgkmcnt(12)
	v_mfma_f32_16x16x32_bf16 v[0:3], v[100:103], v[60:63], v[0:3]
	s_waitcnt vmcnt(7)
	s_waitcnt lgkmcnt(11)
	v_mfma_f32_16x16x32_bf16 v[4:7], v[104:107], v[64:67], v[4:7]
	s_waitcnt lgkmcnt(10)
	v_mfma_f32_16x16x32_bf16 v[0:3], v[108:111], v[64:67], v[0:3]
	s_waitcnt vmcnt(6)
	s_waitcnt lgkmcnt(9)
	v_mfma_f32_16x16x32_bf16 v[4:7], v[112:115], v[68:71], v[4:7]
	s_waitcnt lgkmcnt(8)
	v_mfma_f32_16x16x32_bf16 v[0:3], v[116:119], v[68:71], v[0:3]
	s_waitcnt vmcnt(5)
	s_waitcnt lgkmcnt(7)
	v_mfma_f32_16x16x32_bf16 v[4:7], v[120:123], v[72:75], v[4:7]
	s_waitcnt lgkmcnt(6)
	v_mfma_f32_16x16x32_bf16 v[0:3], v[124:127], v[72:75], v[0:3]
	s_waitcnt vmcnt(4)
	s_waitcnt lgkmcnt(5)
	v_mfma_f32_16x16x32_bf16 v[4:7], v[130:133], v[76:79], v[4:7]
	s_waitcnt lgkmcnt(4)
	v_mfma_f32_16x16x32_bf16 v[0:3], v[134:137], v[76:79], v[0:3]
	s_waitcnt vmcnt(3)
	s_waitcnt lgkmcnt(3)
	v_mfma_f32_16x16x32_bf16 v[4:7], v[138:141], v[80:83], v[4:7]
	s_waitcnt lgkmcnt(2)
	v_mfma_f32_16x16x32_bf16 v[0:3], v[142:145], v[80:83], v[0:3]
	s_waitcnt vmcnt(2)
	s_waitcnt lgkmcnt(1)
	v_mfma_f32_16x16x32_bf16 v[4:7], v[146:149], v[84:87], v[4:7]
	s_waitcnt lgkmcnt(0)
	v_mfma_f32_16x16x32_bf16 v[0:3], v[150:153], v[84:87], v[0:3]
	s_lshl_b32 s6, s4, 11
	s_ashr_i32 s7, s6, 31
	s_lshl_b64 s[6:7], s[6:7], 2
	v_readlane_b32 s14, v245, 14
	v_readlane_b32 s15, v245, 15
	s_add_u32 s6, s14, s6
	s_addc_u32 s7, s15, s7
	v_lshl_add_u64 v[12:13], v[10:11], 2, s[6:7]
	global_load_dword v11, v[12:13], off
	global_load_dword v14, v[12:13], off offset:512
	s_movk_i32 s6, 0x1000
	v_lshlrev_b32_e32 v10, 1, v10
	s_lshl_b64 s[4:5], s[4:5], 14
	v_bfe_u32 v16, v9, 6, 2
	s_waitcnt vmcnt(1)
	v_add_f32_e32 v11, 0, v11
	s_waitcnt vmcnt(0)
	v_add_f32_e32 v11, v11, v14
	global_load_dword v14, v[12:13], off offset:1024
	s_waitcnt vmcnt(0)
	v_add_f32_e32 v11, v11, v14
	global_load_dword v14, v[12:13], off offset:1536
	s_waitcnt vmcnt(0)
	v_add_f32_e32 v11, v11, v14
	global_load_dword v14, v[12:13], off offset:2048
	s_waitcnt vmcnt(0)
	v_add_f32_e32 v11, v11, v14
	global_load_dword v14, v[12:13], off offset:2560
	s_waitcnt vmcnt(0)
	v_add_f32_e32 v11, v11, v14
	global_load_dword v14, v[12:13], off offset:3072
	s_waitcnt vmcnt(0)
	v_add_f32_e32 v11, v11, v14
	global_load_dword v14, v[12:13], off offset:3584
	v_add_co_u32_e32 v12, vcc, s6, v12
	s_movk_i32 s6, 0x110
	s_nop 0
	v_addc_co_u32_e32 v13, vcc, 0, v13, vcc
	s_waitcnt vmcnt(0)
	v_add_f32_e32 v11, v11, v14
	global_load_dword v14, v[12:13], off
	s_waitcnt vmcnt(0)
	v_add_f32_e32 v11, v11, v14
	global_load_dword v14, v[12:13], off offset:512
	s_waitcnt vmcnt(0)
	v_add_f32_e32 v11, v11, v14
	global_load_dword v14, v[12:13], off offset:1024
	s_waitcnt vmcnt(0)
	v_add_f32_e32 v11, v11, v14
	global_load_dword v14, v[12:13], off offset:1536
	s_waitcnt vmcnt(0)
	v_add_f32_e32 v11, v11, v14
	global_load_dword v14, v[12:13], off offset:2048
	s_waitcnt vmcnt(0)
	v_add_f32_e32 v11, v11, v14
	global_load_dword v14, v[12:13], off offset:2560
	s_waitcnt vmcnt(0)
	v_add_f32_e32 v11, v11, v14
	global_load_dword v14, v[12:13], off offset:3072
	s_waitcnt vmcnt(0)
	v_add_f32_e32 v11, v11, v14
	global_load_dword v12, v[12:13], off offset:3584
	s_waitcnt vmcnt(0)
; #define LAS __attribute__((address_space(3)))
; DI bf16_t tobf(float x) { return (bf16_t)(pk2(x, 0.f) & 0xffffu); }
; DI u32x4 pack8(const float* f) { u32x4 w; w.x = pk2(f[0], f[1]); w.y = pk2(f[2], f[3]); w.z = pk2(f[4], f[5]); w.w = pk2(f[6], f[7]); return w; }
; DI float red8(float x) { x = red4(x); x = dpp_add<0x141>(x); return x; }
; #define MFMA16(a, b, c) __builtin_amdgcn_mfma_f32_16x16x32_bf16((a), (b), (c), 0, 0, 0)
; DI float gelu_tanh(float x) { const float u = 0.7978845608f * (x + 0.044715f * x * x * x); return 0.5f * x * (1.f + tanh_fast(u)); }
; DI void compress_item(const Args& a, int l, int item, LAS unsigned char* lds) {
;     ...
; #pragma unroll
;         for (int m = 0; m < 2; ++m)
; #pragma unroll
;             for (int r = 0; r < 4; ++r) hs[(m * 16 + fq * 4 + r) * 136 + c] = tobf(gelu_tanh(acc[m][r] + bias));
;     }
;     __syncthreads();
;     {
;         const int m = wid >> 2, nt = wid & 3;
;         f32x4 acc2 = {0.f, 0.f, 0.f, 0.f};
; #pragma unroll
;         for (int ks = 0; ks < 4; ++ks) {
;             const bf16x8 af = *(const LAS bf16x8*)(hs + (m * 16 + fr) * 136 + ks * 32 + fq * 8);
;             const bf16x8 bf = *(const bf16x8*)(W + W_C2 + (size_t)kv * 8192 + (size_t)(nt * 16 + fr) * 128 + ks * 32 + fq * 8);
;             acc2 = MFMA16(af, bf, acc2);
;         }
; #pragma unroll
;         for (int r = 0; r < 4; ++r) os[(m * 16 + fq * 4 + r) * 64 + nt * 16 + fr] = acc2[r];
;     }
;     __syncthreads();
;     if (tid < 256) {
;         const int rowi = tid >> 3, d0 = (tid & 7) * 8, n = nq * 32 + rowi;
;         float v[8];
; #pragma unroll
;         for (int i = 0; i < 8; ++i) v[i] = os[rowi * 64 + d0 + i];
;         if (kv == 0) {
;             float ss = 0.f;
; #pragma unroll
;             for (int i = 0; i < 8; ++i) ss += v[i] * v[i];
;             ss = red8(ss);
;             const float rstd = rsqrtf(ss * (1.f / 64.f) + 1e-6f);
;             const float* gn = a.in[I_KGAIN] + (l * 3 + 0) * 64 + d0;
; #pragma unroll
;             for (int i = 0; i < 8; ++i) v[i] = (n == 255) ? 0.f : v[i] * rstd * gn[i];
;             *(u32x4*)((bf16_t*)(a.ws + WS_KCN) + ((size_t)bg * 256 + n) * 64 + d0) = pack8(v);
;         } else {
;             bf16_t* vct = (bf16_t*)(a.ws + WS_VCT) + (size_t)bg * 64 * 256;
; #pragma unroll
;             for (int i = 0; i < 8; ++i) vct[(d0 + i) * 256 + n] = tobf(n == 255 ? 0.f : v[i]);
	v_add_f32_e32 v11, v11, v12
	v_add_f32_e32 v4, v4, v11
	v_mul_f32_e32 v12, 0x3d372713, v4
	v_mul_f32_e32 v12, v4, v12
	v_fma_f32 v12, v4, v12, v4
	v_mul_f32_e32 v12, 0x3f4c422a, v12
	v_add_f32_e32 v12, v12, v12
	v_mul_f32_e32 v12, 0x3fb8aa3b, v12
	v_exp_f32_e32 v12, v12
	v_mul_f32_e32 v4, 0.5, v4
	v_add_f32_e32 v5, v5, v11
	v_add_f32_e32 v0, v0, v11
	v_add_f32_e32 v12, 1.0, v12
	v_rcp_f32_e32 v12, v12
	s_nop 0
	v_fma_f32 v12, v12, -2.0, 1.0
	v_add_f32_e32 v12, 1.0, v12
	v_mul_f32_e32 v4, v4, v12
	v_cvt_pk_bf16_f32 v12, v4, s0
	v_mul_u32_u24_e32 v4, 0x440, v20
	v_add3_u32 v4, 0, v10, v4
	v_mul_f32_e32 v10, 0x3d372713, v5
	v_mul_f32_e32 v10, v5, v10
	v_fma_f32 v10, v5, v10, v5
	v_mul_f32_e32 v10, 0x3f4c422a, v10
	v_add_f32_e32 v10, v10, v10
	v_mul_f32_e32 v10, 0x3fb8aa3b, v10
	v_exp_f32_e32 v10, v10
	v_mul_f32_e32 v5, 0.5, v5
	ds_write_b16 v4, v12
	v_add_f32_e32 v10, 1.0, v10
	v_rcp_f32_e32 v10, v10
	s_nop 0
	v_fma_f32 v10, v10, -2.0, 1.0
	v_add_f32_e32 v10, 1.0, v10
	v_mul_f32_e32 v5, v5, v10
	v_cvt_pk_bf16_f32 v5, v5, s0
	ds_write_b16 v4, v5 offset:272
	v_add_f32_e32 v5, v6, v11
	v_mul_f32_e32 v6, 0x3d372713, v5
	v_mul_f32_e32 v6, v5, v6
	v_fma_f32 v6, v5, v6, v5
	v_mul_f32_e32 v6, 0x3f4c422a, v6
	v_add_f32_e32 v6, v6, v6
	v_mul_f32_e32 v6, 0x3fb8aa3b, v6
	v_exp_f32_e32 v6, v6
	v_mul_f32_e32 v5, 0.5, v5
	v_add_f32_e32 v6, 1.0, v6
	v_rcp_f32_e32 v6, v6
	s_nop 0
	v_fma_f32 v6, v6, -2.0, 1.0
	v_add_f32_e32 v6, 1.0, v6
	v_mul_f32_e32 v5, v5, v6
	v_cvt_pk_bf16_f32 v5, v5, s0
	ds_write_b16 v4, v5 offset:544
	v_add_f32_e32 v5, v7, v11
	v_mul_f32_e32 v6, 0x3d372713, v5
	v_mul_f32_e32 v6, v5, v6
	v_fma_f32 v6, v5, v6, v5
	v_mul_f32_e32 v6, 0x3f4c422a, v6
	v_add_f32_e32 v6, v6, v6
	v_mul_f32_e32 v6, 0x3fb8aa3b, v6
	v_exp_f32_e32 v6, v6
	v_mul_f32_e32 v5, 0.5, v5
	v_add_f32_e32 v6, 1.0, v6
	v_rcp_f32_e32 v6, v6
	s_nop 0
	v_fma_f32 v6, v6, -2.0, 1.0
	v_add_f32_e32 v6, 1.0, v6
	v_mul_f32_e32 v5, v5, v6
	v_cvt_pk_bf16_f32 v5, v5, s0
	ds_write_b16 v4, v5 offset:816
	v_mul_f32_e32 v5, 0x3d372713, v0
	v_mul_f32_e32 v5, v0, v5
	v_fma_f32 v5, v0, v5, v0
	v_mul_f32_e32 v5, 0x3f4c422a, v5
	v_add_f32_e32 v5, v5, v5
	v_mul_f32_e32 v5, 0x3fb8aa3b, v5
	v_exp_f32_e32 v5, v5
	v_mul_f32_e32 v0, 0.5, v0
	v_add_f32_e32 v5, 1.0, v5
	v_rcp_f32_e32 v5, v5
	s_nop 0
	v_fma_f32 v5, v5, -2.0, 1.0
	v_add_f32_e32 v5, 1.0, v5
	v_mul_f32_e32 v0, v0, v5
	v_cvt_pk_bf16_f32 v0, v0, s0
	ds_write_b16 v4, v0 offset:4352
	v_add_f32_e32 v0, v1, v11
	v_mul_f32_e32 v1, 0x3d372713, v0
	v_mul_f32_e32 v1, v0, v1
	v_fma_f32 v1, v0, v1, v0
	v_mul_f32_e32 v1, 0x3f4c422a, v1
	v_add_f32_e32 v1, v1, v1
	v_mul_f32_e32 v1, 0x3fb8aa3b, v1
	v_exp_f32_e32 v1, v1
	v_mul_f32_e32 v0, 0.5, v0
	v_add_f32_e32 v1, 1.0, v1
	v_rcp_f32_e32 v1, v1
	s_nop 0
	v_fma_f32 v1, v1, -2.0, 1.0
	v_add_f32_e32 v1, 1.0, v1
	v_mul_f32_e32 v0, v0, v1
	v_cvt_pk_bf16_f32 v0, v0, s0
	ds_write_b16 v4, v0 offset:4624
	v_add_f32_e32 v0, v2, v11
	v_mul_f32_e32 v1, 0x3d372713, v0
	v_mul_f32_e32 v1, v0, v1
	v_fma_f32 v1, v0, v1, v0
	v_mul_f32_e32 v1, 0x3f4c422a, v1
	v_add_f32_e32 v1, v1, v1
	v_mul_f32_e32 v1, 0x3fb8aa3b, v1
	v_exp_f32_e32 v1, v1
	v_mul_f32_e32 v0, 0.5, v0
	v_add_f32_e32 v1, 1.0, v1
	v_rcp_f32_e32 v1, v1
	s_nop 0
	v_fma_f32 v1, v1, -2.0, 1.0
	v_add_f32_e32 v1, 1.0, v1
	v_mul_f32_e32 v0, v0, v1
	v_cvt_pk_bf16_f32 v0, v0, s0
	ds_write_b16 v4, v0 offset:4896
	v_add_f32_e32 v0, v3, v11
	v_mul_f32_e32 v1, 0x3d372713, v0
	v_mul_f32_e32 v1, v0, v1
	v_fma_f32 v1, v0, v1, v0
	v_mul_f32_e32 v1, 0x3f4c422a, v1
	v_add_f32_e32 v1, v1, v1
	v_mul_f32_e32 v1, 0x3fb8aa3b, v1
	v_exp_f32_e32 v1, v1
	v_mul_f32_e32 v0, 0.5, v0
	v_add_f32_e32 v1, 1.0, v1
	v_rcp_f32_e32 v1, v1
	s_nop 0
	v_fma_f32 v1, v1, -2.0, 1.0
	v_add_f32_e32 v1, 1.0, v1
	v_mul_f32_e32 v0, v0, v1
	v_cvt_pk_bf16_f32 v0, v0, s0
	ds_write_b16 v4, v0 offset:5168
	v_ashrrev_i32_e32 v0, 4, v9
	v_and_b32_e32 v17, -16, v0
	v_or_b32_e32 v0, v17, v21
	v_mul_lo_u32 v1, v0, s6
	v_lshlrev_b32_e32 v0, 1, v8
	v_readlane_b32 s6, v245, 52
	v_add3_u32 v8, 0, v1, v0
	v_readlane_b32 s7, v245, 53
	s_add_u32 s4, s6, s4
	v_lshlrev_b32_e32 v1, 8, v21
	s_addc_u32 s5, s7, s5
	v_lshl_or_b32 v128, v16, 12, v1
	v_lshl_add_u64 v[2:3], s[4:5], 0, v[128:129]
	v_mov_b32_e32 v1, v129
	v_lshl_add_u64 v[14:15], v[2:3], 0, v[0:1]
	s_waitcnt lgkmcnt(0)
	s_barrier
	global_load_dwordx4 v[4:7], v[14:15], off
	global_load_dwordx4 v[10:13], v[14:15], off offset:64
	ds_read_b128 v[0:3], v8
	s_waitcnt vmcnt(1) lgkmcnt(0)
	v_mfma_f32_16x16x32_bf16 v[0:3], v[0:3], v[4:7], 0
	ds_read_b128 v[4:7], v8 offset:64
	s_movk_i32 s4, 0x100
	v_cmp_gt_i32_e32 vcc, s4, v9
	s_waitcnt vmcnt(0) lgkmcnt(0)
	v_mfma_f32_16x16x32_bf16 v[0:3], v[4:7], v[10:13], v[0:3]
	global_load_dwordx4 v[10:13], v[14:15], off offset:128
	ds_read_b128 v[4:7], v8 offset:128
	s_waitcnt vmcnt(0) lgkmcnt(0)
	v_mfma_f32_16x16x32_bf16 v[0:3], v[4:7], v[10:13], v[0:3]
	global_load_dwordx4 v[10:13], v[14:15], off offset:192
	ds_read_b128 v[4:7], v8 offset:192
	s_waitcnt vmcnt(0) lgkmcnt(0)
	v_mfma_f32_16x16x32_bf16 v[0:3], v[4:7], v[10:13], v[0:3]
	v_lshlrev_b32_e32 v4, 6, v16
	v_lshlrev_b32_e32 v5, 2, v21
	v_add3_u32 v4, 0, v4, v5
	v_lshlrev_b32_e32 v5, 10, v20
	v_lshlrev_b32_e32 v6, 8, v17
	v_add3_u32 v4, v4, v5, v6
	s_nop 1
	ds_write2st64_b32 v4, v0, v1 offset0:34 offset1:35
	ds_write2st64_b32 v4, v2, v3 offset0:36 offset1:37
	s_waitcnt lgkmcnt(0)
	s_barrier
	s_and_saveexec_b64 s[4:5], vcc
	s_cbranch_execz .LBB0_598
	v_lshlrev_b32_e32 v0, 3, v9
	v_ashrrev_i32_e32 v8, 3, v9
	v_and_b32_e32 v12, 56, v0
	v_lshlrev_b32_e32 v0, 8, v8
	v_lshlrev_b32_e32 v128, 2, v12
	v_add3_u32 v0, 0, v0, v128
	ds_read_b128 v[4:7], v0 offset:8704
	ds_read_b128 v[0:3], v0 offset:8720
	s_and_b32 s6, s11, 7
	v_lshl_add_u32 v8, s6, 5, v8
	s_mov_b64 s[6:7], -1
	s_and_b64 vcc, exec, s[2:3]
	s_cbranch_vccz .LBB0_608
	s_lshl_b32 s2, s13, 15
	v_readlane_b32 s3, v245, 54
	s_add_u32 s2, s3, s2
	v_readlane_b32 s3, v245, 55
	s_movk_i32 s6, 0xff
	v_lshl_add_u32 v10, v12, 8, v8
	s_addc_u32 s3, s3, 0
	s_waitcnt lgkmcnt(1)
	v_cvt_pk_bf16_f32 v9, v4, s0
	v_cmp_eq_u32_e32 vcc, s6, v8
	v_ashrrev_i32_e32 v11, 31, v10
	v_lshl_add_u64 v[10:11], v[10:11], 1, s[2:3]
	v_cndmask_b32_e64 v9, v9, 0, vcc
	global_store_short v[10:11], v9, off
	v_cvt_pk_bf16_f32 v9, v5, s0
	v_cndmask_b32_e64 v9, v9, 0, vcc
	global_store_short v[10:11], v9, off offset:512
	v_cvt_pk_bf16_f32 v9, v6, s0
	v_cndmask_b32_e64 v9, v9, 0, vcc
	global_store_short v[10:11], v9, off offset:1024
	v_cvt_pk_bf16_f32 v9, v7, s0
	v_cndmask_b32_e64 v9, v9, 0, vcc
	global_store_short v[10:11], v9, off offset:1536
	s_waitcnt lgkmcnt(0)
	v_cvt_pk_bf16_f32 v9, v0, s0
	v_cndmask_b32_e64 v9, v9, 0, vcc
	global_store_short v[10:11], v9, off offset:2048
	v_cvt_pk_bf16_f32 v9, v1, s0
	v_cndmask_b32_e64 v9, v9, 0, vcc
	global_store_short v[10:11], v9, off offset:2560
	v_cvt_pk_bf16_f32 v9, v2, s0
	v_cndmask_b32_e64 v9, v9, 0, vcc
	global_store_short v[10:11], v9, off offset:3072
	v_cvt_pk_bf16_f32 v9, v3, s0
	v_cndmask_b32_e64 v9, v9, 0, vcc
	global_store_short v[10:11], v9, off offset:3584
	s_mov_b64 s[6:7], 0
